# first grid barrier (counter discovery): the 16 per-XCD counter loads of each poll iteration issued together with one wait instead of 16 serialized load+vmcnt(0) round trips
# baseline (speedup 1.0000x reference)
; __device__ __forceinline__ unsigned xb_ld(unsigned* p)              { return __hip_atomic_load(p, __ATOMIC_RELAXED, __HIP_MEMORY_SCOPE_AGENT); }
; __device__ __forceinline__ void xcd_barrier_complete(unsigned* bar, unsigned x, unsigned& nloc, unsigned& nx) {
;   const unsigned G = gridDim.x * gridDim.y * gridDim.z;
;   unsigned sum, cnt, mine, sp = 0u;
;   for (;;) {
;     sum = 0u; cnt = 0u; mine = 0u;
; #pragma unroll
;     for (unsigned j = 0; j < 16; ++j) { const unsigned c = xb_ld(&bar[XB_XCNT(j)]); sum += c; cnt += (c > 0u) ? 1u : 0u; mine = (j == x) ? c : mine; }
;     if (sum == G) break;
;     __builtin_amdgcn_s_sleep(1);
;     if ((++sp & 255u) == 0u) { if (xb_ld(&bar[XB_TMO])) break; if (sp > XB_SPIN_CAP) { atomicAdd(&bar[XB_TMO], 1u); break; } }
;   }
;   nloc = mine > 0u ? mine : 1u; nx = cnt > 0u ? cnt : 1u;
; }
.LBB0_702:
	v_readlane_b32 s12, v252, 33
	v_readlane_b32 s13, v252, 34
	v_readlane_b32 s3, v252, 30
	s_mov_b64 s[14:15], -1
	s_waitcnt lgkmcnt(0)
	s_nop 4
	global_load_dword v0, v1, s[12:13] sc1
	global_load_dword v2, v1, s[12:13] offset:256 sc1
	global_load_dword v3, v1, s[12:13] offset:512 sc1
	global_load_dword v4, v1, s[12:13] offset:768 sc1
	global_load_dword v5, v1, s[12:13] offset:1024 sc1
	global_load_dword v6, v1, s[12:13] offset:1280 sc1
	global_load_dword v7, v1, s[12:13] offset:1536 sc1
	global_load_dword v8, v1, s[12:13] offset:1792 sc1
	global_load_dword v9, v1, s[12:13] offset:2048 sc1
	global_load_dword v10, v1, s[12:13] offset:2304 sc1
	global_load_dword v11, v1, s[12:13] offset:2560 sc1
	global_load_dword v12, v1, s[12:13] offset:2816 sc1
	global_load_dword v13, v1, s[12:13] offset:3072 sc1
	global_load_dword v14, v1, s[12:13] offset:3328 sc1
	global_load_dword v15, v1, s[12:13] offset:3584 sc1
	global_load_dword v16, v1, s[12:13] offset:3840 sc1
	s_mov_b64 s[12:13], -1
	s_waitcnt vmcnt(0)
	v_add_u32_e32 v17, v2, v0
	v_add_u32_e32 v17, v17, v3
	v_add_u32_e32 v17, v17, v4
	v_add_u32_e32 v17, v17, v5
	v_add_u32_e32 v17, v17, v6
	v_add_u32_e32 v17, v17, v7
	v_add_u32_e32 v17, v17, v8
	v_add_u32_e32 v17, v17, v9
	v_add_u32_e32 v17, v17, v10
	v_add_u32_e32 v17, v17, v11
	v_add_u32_e32 v17, v17, v12
	v_add_u32_e32 v17, v17, v13
	v_add_u32_e32 v17, v17, v14
	v_add_u32_e32 v17, v17, v15
	v_add_u32_e32 v17, v17, v16
	v_cmp_eq_u32_e32 vcc, s3, v17
	s_cbranch_vccnz .LBB0_701
	s_and_b32 s3, s2, 0xff
	s_cmp_eq_u32 s3, 0
	s_mov_b64 s[18:19], -1
	s_sleep 1
	s_cbranch_scc1 .LBB0_706
	s_and_b64 vcc, exec, s[18:19]
	s_cbranch_vccz .LBB0_701
